# v23 with the trailing-half loop shifted by 48 bytes (placement only)
# baseline (speedup 1.0000x reference)
.LqT_rescale:
	s_mov_b32 s98, 0
	ds_bpermute_b32 v129, v210, v128
	s_waitcnt lgkmcnt(0)
	v_max_f32_e32 v129, v129, v129
	v_max_f32_e32 v128, v128, v129
	v_cmp_lt_f32_e32 vcc, s88, v128
	s_nop 0
	s_nop 0
	v_cndmask_b32_e32 v128, 0, v128, vcc
	v_exp_f32_e64 v130, -v128
	v_pk_add_f32 v[64:65], v[64:65], v[128:129] op_sel_hi:[1,0] neg_lo:[0,1] neg_hi:[0,1]
	v_pk_add_f32 v[80:81], v[80:81], v[128:129] op_sel_hi:[1,0] neg_lo:[0,1] neg_hi:[0,1]
	v_pk_add_f32 v[66:67], v[66:67], v[128:129] op_sel_hi:[1,0] neg_lo:[0,1] neg_hi:[0,1]
	v_pk_mul_f32 v[46:47], v[46:47], v[130:131] op_sel_hi:[1,0]
	v_pk_mul_f32 v[44:45], v[44:45], v[130:131] op_sel_hi:[1,0]
	v_pk_mul_f32 v[42:43], v[42:43], v[130:131] op_sel_hi:[1,0]
	v_pk_mul_f32 v[40:41], v[40:41], v[130:131] op_sel_hi:[1,0]
	v_pk_mul_f32 v[38:39], v[38:39], v[130:131] op_sel_hi:[1,0]
	v_pk_mul_f32 v[36:37], v[36:37], v[130:131] op_sel_hi:[1,0]
	v_pk_mul_f32 v[34:35], v[34:35], v[130:131] op_sel_hi:[1,0]
	v_pk_mul_f32 v[32:33], v[32:33], v[130:131] op_sel_hi:[1,0]
	v_pk_mul_f32 v[62:63], v[62:63], v[130:131] op_sel_hi:[1,0]
	v_pk_mul_f32 v[60:61], v[60:61], v[130:131] op_sel_hi:[1,0]
	v_pk_mul_f32 v[58:59], v[58:59], v[130:131] op_sel_hi:[1,0]
	v_pk_mul_f32 v[56:57], v[56:57], v[130:131] op_sel_hi:[1,0]
	v_pk_mul_f32 v[54:55], v[54:55], v[130:131] op_sel_hi:[1,0]
	v_pk_mul_f32 v[52:53], v[52:53], v[130:131] op_sel_hi:[1,0]
	v_pk_mul_f32 v[50:51], v[50:51], v[130:131] op_sel_hi:[1,0]
	v_pk_mul_f32 v[48:49], v[48:49], v[130:131] op_sel_hi:[1,0]
	v_pk_mul_f32 v[30:31], v[30:31], v[130:131] op_sel_hi:[1,0]
	v_pk_mul_f32 v[28:29], v[28:29], v[130:131] op_sel_hi:[1,0]
	v_pk_mul_f32 v[26:27], v[26:27], v[130:131] op_sel_hi:[1,0]
	v_pk_mul_f32 v[24:25], v[24:25], v[130:131] op_sel_hi:[1,0]
	v_pk_mul_f32 v[22:23], v[22:23], v[130:131] op_sel_hi:[1,0]
	v_pk_mul_f32 v[20:21], v[20:21], v[130:131] op_sel_hi:[1,0]
	v_pk_mul_f32 v[18:19], v[18:19], v[130:131] op_sel_hi:[1,0]
	v_pk_mul_f32 v[16:17], v[16:17], v[130:131] op_sel_hi:[1,0]
	v_pk_mul_f32 v[14:15], v[14:15], v[130:131] op_sel_hi:[1,0]
	v_pk_mul_f32 v[12:13], v[12:13], v[130:131] op_sel_hi:[1,0]
	v_pk_mul_f32 v[10:11], v[10:11], v[130:131] op_sel_hi:[1,0]
	v_pk_mul_f32 v[8:9], v[8:9], v[130:131] op_sel_hi:[1,0]
	v_pk_mul_f32 v[6:7], v[6:7], v[130:131] op_sel_hi:[1,0]
	v_pk_mul_f32 v[4:5], v[4:5], v[130:131] op_sel_hi:[1,0]
	v_pk_mul_f32 v[2:3], v[2:3], v[130:131] op_sel_hi:[1,0]
	v_pk_mul_f32 v[0:1], v[0:1], v[130:131] op_sel_hi:[1,0]
	v_mov_b32_e32 v131, v128
	v_pk_add_f32 v[82:83], v[82:83], v[128:129] op_sel_hi:[1,0] neg_lo:[0,1] neg_hi:[0,1]
	v_pk_add_f32 v[68:69], v[68:69], v[128:129] op_sel_hi:[1,0] neg_lo:[0,1] neg_hi:[0,1]
	v_pk_add_f32 v[84:85], v[84:85], v[128:129] op_sel_hi:[1,0] neg_lo:[0,1] neg_hi:[0,1]
	v_pk_add_f32 v[70:71], v[70:71], v[128:129] op_sel_hi:[1,0] neg_lo:[0,1] neg_hi:[0,1]
	v_pk_add_f32 v[86:87], v[86:87], v[128:129] op_sel_hi:[1,0] neg_lo:[0,1] neg_hi:[0,1]
	v_pk_add_f32 v[72:73], v[72:73], v[128:129] op_sel_hi:[1,0] neg_lo:[0,1] neg_hi:[0,1]
	v_pk_add_f32 v[88:89], v[88:89], v[128:129] op_sel_hi:[1,0] neg_lo:[0,1] neg_hi:[0,1]
	v_pk_add_f32 v[74:75], v[74:75], v[128:129] op_sel_hi:[1,0] neg_lo:[0,1] neg_hi:[0,1]
	v_pk_add_f32 v[90:91], v[90:91], v[128:129] op_sel_hi:[1,0] neg_lo:[0,1] neg_hi:[0,1]
	v_pk_add_f32 v[76:77], v[76:77], v[128:129] op_sel_hi:[1,0] neg_lo:[0,1] neg_hi:[0,1]
	v_pk_add_f32 v[92:93], v[92:93], v[128:129] op_sel_hi:[1,0] neg_lo:[0,1] neg_hi:[0,1]
	v_pk_add_f32 v[78:79], v[78:79], v[128:129] op_sel_hi:[1,0] neg_lo:[0,1] neg_hi:[0,1]
	v_pk_add_f32 v[94:95], v[94:95], v[128:129] op_sel_hi:[1,0] neg_lo:[0,1] neg_hi:[0,1]
	v_pk_add_f32 v[128:129], v[206:207], v[130:131]
	v_pk_mul_f32 v[206:207], v[206:207], v[130:131]
	s_nop 0
	v_mov_b32_e32 v207, v129
	s_branch .LqT_g0
	s_nop 0
	s_nop 0
	s_nop 0
.LBB0_284:
	s_setprio 1
	s_add_i32 s13, s26, 0xfffff7a6
	s_cmp_lt_u32 s13, 0xfffffeed
	s_mov_b64 s[22:23], -1
	s_cbranch_scc1 .LBB0_286
	v_add_u32_e32 v64, 0x22fc, v165
	v_add_u32_e32 v66, 0x237c, v165
	v_add_u32_e32 v67, 0x2304, v165
	v_add_u32_e32 v68, 0x2384, v165
	ds_read2_b32 v[64:65], v64 offset1:1
	ds_read2_b32 v[80:81], v66 offset1:1
	ds_read2_b32 v[66:67], v67 offset1:1
	ds_read2_b32 v[82:83], v68 offset1:1
	v_add_u32_e32 v68, 0x231c, v165
	v_add_u32_e32 v70, 0x239c, v165
	v_add_u32_e32 v71, 0x2324, v165
	v_add_u32_e32 v72, 0x23a4, v165
	ds_read2_b32 v[68:69], v68 offset1:1
	ds_read2_b32 v[84:85], v70 offset1:1
	ds_read2_b32 v[70:71], v71 offset1:1
	ds_read2_b32 v[86:87], v72 offset1:1
	v_add_u32_e32 v72, 0x233c, v165
	v_add_u32_e32 v74, 0x23bc, v165
	v_add_u32_e32 v75, 0x2344, v165
	v_add_u32_e32 v76, 0x23c4, v165
	ds_read2_b32 v[72:73], v72 offset1:1
	ds_read2_b32 v[88:89], v74 offset1:1
	ds_read2_b32 v[74:75], v75 offset1:1
	ds_read2_b32 v[90:91], v76 offset1:1
	v_add_u32_e32 v76, 0x235c, v165
	v_add_u32_e32 v92, 0x23dc, v165
	v_add_u32_e32 v78, 0x2364, v165
	v_add_u32_e32 v93, 0x23e4, v165
	ds_read2_b32 v[76:77], v76 offset1:1
	ds_read2_b32 v[78:79], v78 offset1:1
	ds_read2_b32 v[94:95], v93 offset1:1
	ds_read2_b32 v[92:93], v92 offset1:1
	s_waitcnt lgkmcnt(0)
	v_sub_f32_e32 v65, v65, v207
	v_sub_f32_e32 v66, v66, v207
	v_sub_f32_e32 v67, v67, v207
	v_sub_f32_e32 v68, v68, v207
	v_sub_f32_e32 v69, v69, v207
	v_sub_f32_e32 v70, v70, v207
	v_sub_f32_e32 v71, v71, v207
	v_sub_f32_e32 v72, v72, v207
	v_sub_f32_e32 v73, v73, v207
	v_sub_f32_e32 v74, v74, v207
	v_sub_f32_e32 v75, v75, v207
	v_sub_f32_e32 v76, v76, v207
	v_sub_f32_e32 v77, v77, v207
	v_sub_f32_e32 v78, v78, v207
	v_sub_f32_e32 v79, v79, v207
	v_sub_f32_e32 v64, v64, v207
	v_sub_f32_e32 v81, v81, v207
	v_sub_f32_e32 v82, v82, v207
	v_sub_f32_e32 v83, v83, v207
	v_sub_f32_e32 v84, v84, v207
	v_sub_f32_e32 v85, v85, v207
	v_sub_f32_e32 v86, v86, v207
	v_sub_f32_e32 v87, v87, v207
	v_sub_f32_e32 v88, v88, v207
	v_sub_f32_e32 v89, v89, v207
	v_sub_f32_e32 v90, v90, v207
	v_sub_f32_e32 v91, v91, v207
	v_sub_f32_e32 v92, v92, v207
	v_sub_f32_e32 v93, v93, v207
	v_sub_f32_e32 v94, v94, v207
	v_sub_f32_e32 v95, v95, v207
	v_sub_f32_e32 v80, v80, v207
	s_mov_b64 s[22:23], 0
